# mprep: V-tile loads issued before the gate scans (held in spare VGPRs) instead of a separate round trip after the K_w^T transposition; on top of v58
# baseline (speedup 1.0000x reference)
.LBB0_264:
	s_or_b64 exec, exec, s[6:7]
	s_mul_i32 s98, s95, 0x1800
	s_lshl_b32 s100, s2, 9
	s_add_u32 s98, s98, s52
	s_addc_u32 s99, s53, 0
	s_add_u32 s98, s98, s100
	s_addc_u32 s99, s99, 0
	s_add_u32 s98, s98, 0x1000
	s_addc_u32 s99, s99, 0
	v_lshrrev_b32_e32 v248, 5, v182
	v_and_b32_e32 v249, 31, v182
	v_mul_u32_u24_e32 v248, 0x1800, v248
	v_lshl_add_u32 v248, v249, 4, v248
	global_load_dwordx4 v[184:187], v248, s[98:99] nt
	s_add_u32 s98, s98, 0x18000
	s_addc_u32 s99, s99, 0
	global_load_dwordx4 v[188:191], v248, s[98:99] nt
	s_add_u32 s98, s98, 0x18000
	s_addc_u32 s99, s99, 0
	global_load_dwordx4 v[192:195], v248, s[98:99] nt
	s_add_u32 s98, s98, 0x18000
	s_addc_u32 s99, s99, 0
	global_load_dwordx4 v[196:199], v248, s[98:99] nt
	s_add_u32 s98, s98, 0x18000
	s_addc_u32 s99, s99, 0
	global_load_dwordx4 v[200:203], v248, s[98:99] nt
	s_add_u32 s98, s98, 0x18000
	s_addc_u32 s99, s99, 0
	global_load_dwordx4 v[204:207], v248, s[98:99] nt
	s_add_u32 s98, s98, 0x18000
	s_addc_u32 s99, s99, 0
	global_load_dwordx4 v[208:211], v248, s[98:99] nt
	s_add_u32 s98, s98, 0x18000
	s_addc_u32 s99, s99, 0
	global_load_dwordx4 v[212:215], v248, s[98:99] nt
	s_add_u32 s98, s98, 0x18000
	s_addc_u32 s99, s99, 0
	global_load_dwordx4 v[216:219], v248, s[98:99] nt
	s_add_u32 s98, s98, 0x18000
	s_addc_u32 s99, s99, 0
	global_load_dwordx4 v[220:223], v248, s[98:99] nt
	s_add_u32 s98, s98, 0x18000
	s_addc_u32 s99, s99, 0
	global_load_dwordx4 v[224:227], v248, s[98:99] nt
	s_add_u32 s98, s98, 0x18000
	s_addc_u32 s99, s99, 0
	global_load_dwordx4 v[228:231], v248, s[98:99] nt
	s_add_u32 s98, s98, 0x18000
	s_addc_u32 s99, s99, 0
	global_load_dwordx4 v[232:235], v248, s[98:99] nt
	s_add_u32 s98, s98, 0x18000
	s_addc_u32 s99, s99, 0
	global_load_dwordx4 v[236:239], v248, s[98:99] nt
	s_add_u32 s98, s98, 0x18000
	s_addc_u32 s99, s99, 0
	global_load_dwordx4 v[240:243], v248, s[98:99] nt
	s_add_u32 s98, s98, 0x18000
	s_addc_u32 s99, s99, 0
	global_load_dwordx4 v[244:247], v248, s[98:99] nt
	s_add_i32 s0, 0, 0x21000
	v_lshl_add_u32 v4, v96, 2, s0
	v_add_u32_e32 v5, 0xffffff00, v96
	s_movk_i32 s0, 0xff00
	v_cmp_lt_u32_e32 vcc, s0, v5
	v_mov_b32_e32 v6, 0
	s_waitcnt lgkmcnt(0)
	s_barrier
	s_and_saveexec_b64 s[6:7], vcc
	v_add_u32_e32 v6, -4, v4
	ds_read_b32 v6, v6
	s_or_b64 exec, exec, s[6:7]
	s_waitcnt lgkmcnt(0)
	s_barrier
	s_and_saveexec_b64 s[6:7], s[4:5]
	v_add_f32_e32 v3, v3, v6
	ds_write_b32 v4, v3
	s_or_b64 exec, exec, s[6:7]
	s_movk_i32 s0, 0xff01
	v_cmp_lt_u32_e64 s[6:7], s0, v5
	v_mov_b32_e32 v6, 0
	s_waitcnt lgkmcnt(0)
	s_barrier
	s_and_saveexec_b64 s[8:9], s[6:7]
	v_add_u32_e32 v6, -8, v4
	ds_read_b32 v6, v6
	s_or_b64 exec, exec, s[8:9]
	s_waitcnt lgkmcnt(0)
	s_barrier
	s_and_saveexec_b64 s[8:9], s[4:5]
	v_add_f32_e32 v3, v3, v6
	ds_write_b32 v4, v3
	s_or_b64 exec, exec, s[8:9]
	s_movk_i32 s0, 0xff03
	v_cmp_lt_u32_e64 s[8:9], s0, v5
	v_mov_b32_e32 v6, 0
	s_waitcnt lgkmcnt(0)
	s_barrier
	s_and_saveexec_b64 s[10:11], s[8:9]
	v_add_u32_e32 v6, -16, v4
	ds_read_b32 v6, v6
	s_or_b64 exec, exec, s[10:11]
	s_waitcnt lgkmcnt(0)
	s_barrier
	s_and_saveexec_b64 s[10:11], s[4:5]
	v_add_f32_e32 v3, v3, v6
	ds_write_b32 v4, v3
	s_or_b64 exec, exec, s[10:11]
	s_movk_i32 s0, 0xff07
	v_cmp_lt_u32_e64 s[10:11], s0, v5
	v_mov_b32_e32 v6, 0
	s_waitcnt lgkmcnt(0)
	s_barrier
	s_and_saveexec_b64 s[12:13], s[10:11]
	v_subrev_u32_e32 v6, 32, v4
	ds_read_b32 v6, v6
	s_or_b64 exec, exec, s[12:13]
	s_waitcnt lgkmcnt(0)
	s_barrier
	s_and_saveexec_b64 s[12:13], s[4:5]
	v_add_f32_e32 v3, v3, v6
	ds_write_b32 v4, v3
	s_or_b64 exec, exec, s[12:13]
	s_movk_i32 s0, 0xff0f
	v_cmp_lt_u32_e64 s[12:13], s0, v5
	v_mov_b32_e32 v6, 0
	s_waitcnt lgkmcnt(0)
	s_barrier
	s_and_saveexec_b64 s[14:15], s[12:13]
	v_subrev_u32_e32 v6, 64, v4
	ds_read_b32 v6, v6
	s_or_b64 exec, exec, s[14:15]
	s_waitcnt lgkmcnt(0)
	s_barrier
	s_and_saveexec_b64 s[14:15], s[4:5]
	v_add_f32_e32 v3, v3, v6
	ds_write_b32 v4, v3
	s_or_b64 exec, exec, s[14:15]
	s_movk_i32 s0, 0xff1f
	v_cmp_lt_u32_e64 s[14:15], s0, v5
	v_mov_b32_e32 v6, 0
	s_waitcnt lgkmcnt(0)
	s_barrier
	s_and_saveexec_b64 s[16:17], s[14:15]
	v_add_u32_e32 v6, 0xffffff80, v4
	ds_read_b32 v6, v6
	s_or_b64 exec, exec, s[16:17]
	s_waitcnt lgkmcnt(0)
	s_barrier
	s_and_saveexec_b64 s[16:17], s[4:5]
	v_add_f32_e32 v3, v3, v6
	ds_write_b32 v4, v3
	s_or_b64 exec, exec, s[16:17]
	s_movk_i32 s0, 0xff3f
	v_cmp_lt_u32_e64 s[16:17], s0, v5
	v_mov_b32_e32 v6, 0
	s_waitcnt lgkmcnt(0)
	s_barrier
	s_and_saveexec_b64 s[18:19], s[16:17]
	v_add_u32_e32 v6, 0xffffff00, v4
	ds_read_b32 v6, v6
	s_or_b64 exec, exec, s[18:19]
	s_waitcnt lgkmcnt(0)
	s_barrier
	s_and_saveexec_b64 s[18:19], s[4:5]
	v_add_f32_e32 v3, v3, v6
	ds_write_b32 v4, v3
	s_or_b64 exec, exec, s[18:19]
	s_movk_i32 s0, 0xff7f
	v_cmp_lt_u32_e64 s[18:19], s0, v5
	v_mov_b32_e32 v5, 0
	s_waitcnt lgkmcnt(0)
	s_barrier
	s_and_saveexec_b64 s[40:41], s[18:19]
	v_add_u32_e32 v5, 0xfffffe00, v4
	ds_read_b32 v5, v5
	s_or_b64 exec, exec, s[40:41]
	s_waitcnt lgkmcnt(0)
	s_barrier
	s_and_saveexec_b64 s[40:41], s[4:5]
	v_add_f32_e32 v3, v3, v5
	ds_write_b32 v4, v3
	s_or_b64 exec, exec, s[40:41]
	v_mov_b32_e32 v4, 0
	s_waitcnt lgkmcnt(0)
	s_barrier
	s_and_saveexec_b64 s[40:41], s[4:5]
	s_cbranch_execz .LBB0_298
	v_add_u32_e32 v5, 0x21400, v97
	s_waitcnt vmcnt(16)
	v_sub_f32_e32 v4, v2, v3
	ds_write_b32 v5, v4
.LBB0_298:
	s_or_b64 exec, exec, s[40:41]
	s_add_i32 s0, 0, 0x21400
	v_lshl_add_u32 v5, v96, 2, s0
	v_mov_b32_e32 v6, 0xff800000
	s_waitcnt lgkmcnt(0)
	s_barrier
	s_and_saveexec_b64 s[40:41], vcc
	s_cbranch_execz .LBB0_300
	s_waitcnt vmcnt(16)
	v_add_u32_e32 v2, -4, v5
	ds_read_b32 v6, v2
.LBB0_300:
	s_or_b64 exec, exec, s[40:41]
	s_waitcnt vmcnt(16)
	v_mov_b32_e32 v2, v4
	s_waitcnt lgkmcnt(0)
	s_barrier
	s_and_saveexec_b64 s[40:41], s[4:5]
	v_max_f32_e32 v2, v6, v6
	v_max_f32_e32 v6, v4, v4
	v_max_f32_e32 v2, v6, v2
	ds_write_b32 v5, v2
	s_or_b64 exec, exec, s[40:41]
	v_mov_b32_e32 v6, 0xff800000
	s_waitcnt lgkmcnt(0)
	s_barrier
	s_and_saveexec_b64 s[40:41], s[6:7]
	v_add_u32_e32 v6, -8, v5
	ds_read_b32 v6, v6
	s_or_b64 exec, exec, s[40:41]
	s_waitcnt lgkmcnt(0)
	s_barrier
	s_and_saveexec_b64 s[6:7], s[4:5]
	v_max_f32_e32 v6, v6, v6
	v_max_f32_e32 v2, v2, v2
	v_max_f32_e32 v2, v2, v6
	ds_write_b32 v5, v2
	s_or_b64 exec, exec, s[6:7]
	v_mov_b32_e32 v6, 0xff800000
	s_waitcnt lgkmcnt(0)
	s_barrier
	s_and_saveexec_b64 s[6:7], s[8:9]
	v_add_u32_e32 v6, -16, v5
	ds_read_b32 v6, v6
	s_or_b64 exec, exec, s[6:7]
	s_waitcnt lgkmcnt(0)
	s_barrier
	s_and_saveexec_b64 s[6:7], s[4:5]
	v_max_f32_e32 v6, v6, v6
	v_max_f32_e32 v2, v2, v2
	v_max_f32_e32 v2, v2, v6
	ds_write_b32 v5, v2
	s_or_b64 exec, exec, s[6:7]
	v_mov_b32_e32 v6, 0xff800000
	s_waitcnt lgkmcnt(0)
	s_barrier
	s_and_saveexec_b64 s[6:7], s[10:11]
	v_subrev_u32_e32 v6, 32, v5
	ds_read_b32 v6, v6
	s_or_b64 exec, exec, s[6:7]
	s_waitcnt lgkmcnt(0)
	s_barrier
	s_and_saveexec_b64 s[6:7], s[4:5]
	v_max_f32_e32 v6, v6, v6
	v_max_f32_e32 v2, v2, v2
	v_max_f32_e32 v2, v2, v6
	ds_write_b32 v5, v2
	s_or_b64 exec, exec, s[6:7]
	v_mov_b32_e32 v6, 0xff800000
	s_waitcnt lgkmcnt(0)
	s_barrier
	s_and_saveexec_b64 s[6:7], s[12:13]
	v_subrev_u32_e32 v6, 64, v5
	ds_read_b32 v6, v6
	s_or_b64 exec, exec, s[6:7]
	s_waitcnt lgkmcnt(0)
	s_barrier
	s_and_saveexec_b64 s[6:7], s[4:5]
	v_max_f32_e32 v6, v6, v6
	v_max_f32_e32 v2, v2, v2
	v_max_f32_e32 v2, v2, v6
	ds_write_b32 v5, v2
	s_or_b64 exec, exec, s[6:7]
	v_mov_b32_e32 v6, 0xff800000
	s_waitcnt lgkmcnt(0)
	s_barrier
	s_and_saveexec_b64 s[6:7], s[14:15]
	v_add_u32_e32 v6, 0xffffff80, v5
	ds_read_b32 v6, v6
	s_or_b64 exec, exec, s[6:7]
	s_waitcnt lgkmcnt(0)
	s_barrier
	s_and_saveexec_b64 s[6:7], s[4:5]
	v_max_f32_e32 v6, v6, v6
	v_max_f32_e32 v2, v2, v2
	v_max_f32_e32 v2, v2, v6
	ds_write_b32 v5, v2
	s_or_b64 exec, exec, s[6:7]
	v_mov_b32_e32 v6, 0xff800000
	s_waitcnt lgkmcnt(0)
	s_barrier
	s_and_saveexec_b64 s[6:7], s[16:17]
	v_add_u32_e32 v6, 0xffffff00, v5
	ds_read_b32 v6, v6
	s_or_b64 exec, exec, s[6:7]
	s_waitcnt lgkmcnt(0)
	s_barrier
	s_and_saveexec_b64 s[6:7], s[4:5]
	v_max_f32_e32 v6, v6, v6
	v_max_f32_e32 v2, v2, v2
	v_max_f32_e32 v2, v2, v6
	ds_write_b32 v5, v2
	s_or_b64 exec, exec, s[6:7]
	v_mov_b32_e32 v6, 0xff800000
	s_waitcnt lgkmcnt(0)
	s_barrier
	s_and_saveexec_b64 s[6:7], s[18:19]
	v_add_u32_e32 v6, 0xfffffe00, v5
	ds_read_b32 v6, v6
	s_or_b64 exec, exec, s[6:7]
	s_waitcnt lgkmcnt(0)
	s_barrier
	s_and_saveexec_b64 s[6:7], s[4:5]
	v_max_f32_e32 v6, v6, v6
	v_max_f32_e32 v2, v2, v2
	v_max_f32_e32 v2, v2, v6
	ds_write_b32 v5, v2
	s_or_b64 exec, exec, s[6:7]
	v_mov_b32_e32 v5, s87
	s_waitcnt lgkmcnt(0)
	s_barrier
	v_mov_b32_e32 v7, s88
	ds_read_b32 v6, v5
	ds_read_b32 v5, v7
	s_and_saveexec_b64 s[6:7], s[4:5]
	s_cbranch_execz .LBB0_332
	v_lshlrev_b64 v[0:1], 4, v[0:1]
	v_lshl_or_b32 v0, s2, 2, v0
	v_lshl_add_u64 v[8:9], s[62:63], 0, v[0:1]
	global_store_dword v[8:9], v3, off
	s_waitcnt lgkmcnt(1)
	v_sub_f32_e32 v3, v4, v6
	v_mul_f32_e32 v3, 0x3fb8aa3b, v3
	v_exp_f32_e32 v3, v3
	v_lshl_add_u64 v[8:9], s[74:75], 0, v[0:1]
	v_lshl_add_u64 v[0:1], s[28:29], 0, v[0:1]
	global_store_dword v[0:1], v2, off
	v_add_u32_e32 v0, 0x21800, v97
	global_store_dword v[8:9], v4, off
	ds_write_b32 v0, v3

.LBB0_398:
	s_or_b64 exec, exec, s[8:9]
	v_add_u32_e32 v5, s95, v103
	v_mov_b64_e32 v[2:3], s[52:53]
	v_mad_i64_i32 v[6:7], s[0:1], v5, s90, v[2:3]
	v_add_u32_e32 v5, 0x200, v96
	s_lshl_b32 s36, s33, 1
	v_ashrrev_i32_e32 v5, 5, v5
	v_lshl_add_u64 v[6:7], v[6:7], 0, s[36:37]
	v_lshlrev_b32_e32 v128, 1, v131
	v_add_u32_e32 v8, s95, v5
	v_add_u32_e32 v14, 0x400, v96
	v_lshl_add_u64 v[6:7], v[6:7], 0, v[128:129]
	v_mad_i64_i32 v[8:9], s[0:1], v8, s90, v[2:3]
	v_ashrrev_i32_e32 v72, 5, v14
	v_add_co_u32_e32 v6, vcc, 0x1000, v6
	v_lshl_add_u64 v[8:9], v[8:9], 0, s[36:37]
	v_add_u32_e32 v14, s95, v72
	v_add_u32_e32 v16, 0x600, v96
	v_addc_co_u32_e32 v7, vcc, 0, v7, vcc
	v_lshl_add_u64 v[8:9], v[8:9], 0, v[128:129]
	v_mad_i64_i32 v[14:15], s[0:1], v14, s90, v[2:3]
	v_ashrrev_i32_e32 v73, 5, v16
	v_add_co_u32_e32 v10, vcc, 0x1000, v8
	v_lshl_add_u64 v[14:15], v[14:15], 0, s[36:37]
	v_add_u32_e32 v16, s95, v73
	v_add_u32_e32 v22, 0x800, v96
	v_addc_co_u32_e32 v11, vcc, 0, v9, vcc
	v_lshl_add_u64 v[14:15], v[14:15], 0, v[128:129]
	v_mad_i64_i32 v[16:17], s[0:1], v16, s90, v[2:3]
	v_ashrrev_i32_e32 v74, 5, v22
	v_add_co_u32_e32 v14, vcc, 0x1000, v14
	v_lshl_add_u64 v[16:17], v[16:17], 0, s[36:37]
	v_add_u32_e32 v22, s95, v74
	v_add_u32_e32 v24, 0xa00, v96
	v_addc_co_u32_e32 v15, vcc, 0, v15, vcc
	v_lshl_add_u64 v[16:17], v[16:17], 0, v[128:129]
	v_mad_i64_i32 v[22:23], s[0:1], v22, s90, v[2:3]
	v_ashrrev_i32_e32 v75, 5, v24
	v_add_co_u32_e32 v18, vcc, 0x1000, v16
	v_lshl_add_u64 v[22:23], v[22:23], 0, s[36:37]
	v_add_u32_e32 v24, s95, v75
	v_add_u32_e32 v30, 0xc00, v96
	v_addc_co_u32_e32 v19, vcc, 0, v17, vcc
	v_lshl_add_u64 v[22:23], v[22:23], 0, v[128:129]
	v_mad_i64_i32 v[24:25], s[0:1], v24, s90, v[2:3]
	v_ashrrev_i32_e32 v76, 5, v30
	v_add_co_u32_e32 v22, vcc, 0x1000, v22
	v_lshl_add_u64 v[24:25], v[24:25], 0, s[36:37]
	v_add_u32_e32 v30, s95, v76
	v_add_u32_e32 v32, 0xe00, v96
	v_addc_co_u32_e32 v23, vcc, 0, v23, vcc
	v_lshl_add_u64 v[24:25], v[24:25], 0, v[128:129]
	v_mad_i64_i32 v[30:31], s[0:1], v30, s90, v[2:3]
	v_ashrrev_i32_e32 v77, 5, v32
	v_add_co_u32_e32 v26, vcc, 0x1000, v24
	v_lshl_add_u64 v[30:31], v[30:31], 0, s[36:37]
	v_add_u32_e32 v32, s95, v77
	v_add_u32_e32 v38, 0x1000, v96
	v_addc_co_u32_e32 v27, vcc, 0, v25, vcc
	v_lshl_add_u64 v[30:31], v[30:31], 0, v[128:129]
	v_mad_i64_i32 v[32:33], s[0:1], v32, s90, v[2:3]
	v_ashrrev_i32_e32 v78, 5, v38
	v_add_co_u32_e32 v30, vcc, 0x1000, v30
	v_lshl_add_u64 v[32:33], v[32:33], 0, s[36:37]
	v_add_u32_e32 v38, s95, v78
	v_add_u32_e32 v40, 0x1200, v96
	v_addc_co_u32_e32 v31, vcc, 0, v31, vcc
	v_lshl_add_u64 v[32:33], v[32:33], 0, v[128:129]
	v_mad_i64_i32 v[38:39], s[0:1], v38, s90, v[2:3]
	v_ashrrev_i32_e32 v79, 5, v40
	v_add_co_u32_e32 v34, vcc, 0x1000, v32
	v_lshl_add_u64 v[38:39], v[38:39], 0, s[36:37]
	v_add_u32_e32 v40, s95, v79
	v_add_u32_e32 v46, 0x1400, v96
	v_addc_co_u32_e32 v35, vcc, 0, v33, vcc
	v_lshl_add_u64 v[38:39], v[38:39], 0, v[128:129]
	v_mad_i64_i32 v[40:41], s[0:1], v40, s90, v[2:3]
	v_ashrrev_i32_e32 v80, 5, v46
	v_add_co_u32_e32 v38, vcc, 0x1000, v38
	v_lshl_add_u64 v[40:41], v[40:41], 0, s[36:37]
	v_add_u32_e32 v46, s95, v80
	v_add_u32_e32 v48, 0x1600, v96
	v_addc_co_u32_e32 v39, vcc, 0, v39, vcc
	v_lshl_add_u64 v[40:41], v[40:41], 0, v[128:129]
	v_mad_i64_i32 v[46:47], s[0:1], v46, s90, v[2:3]
	v_ashrrev_i32_e32 v81, 5, v48
	v_add_co_u32_e32 v42, vcc, 0x1000, v40
	v_lshl_add_u64 v[46:47], v[46:47], 0, s[36:37]
	v_add_u32_e32 v48, s95, v81
	v_add_u32_e32 v54, 0x1800, v96
	s_barrier
	s_nop 0
	v_addc_co_u32_e32 v43, vcc, 0, v41, vcc
	v_lshl_add_u64 v[46:47], v[46:47], 0, v[128:129]
	v_mad_i64_i32 v[48:49], s[0:1], v48, s90, v[2:3]
	v_ashrrev_i32_e32 v82, 5, v54
	v_add_co_u32_e32 v46, vcc, 0x1000, v46
	v_lshl_add_u64 v[48:49], v[48:49], 0, s[36:37]
	v_add_u32_e32 v54, s95, v82
	v_add_u32_e32 v56, 0x1a00, v96
	s_nop 0
	v_addc_co_u32_e32 v47, vcc, 0, v47, vcc
	v_lshl_add_u64 v[48:49], v[48:49], 0, v[128:129]
	v_mad_i64_i32 v[54:55], s[0:1], v54, s90, v[2:3]
	v_ashrrev_i32_e32 v83, 5, v56
	v_add_co_u32_e32 v50, vcc, 0x1000, v48
	v_lshl_add_u64 v[54:55], v[54:55], 0, s[36:37]
	v_add_u32_e32 v56, s95, v83
	v_add_u32_e32 v62, 0x1c00, v96
	s_nop 0
	v_addc_co_u32_e32 v51, vcc, 0, v49, vcc
	v_lshl_add_u64 v[54:55], v[54:55], 0, v[128:129]
	v_mad_i64_i32 v[56:57], s[0:1], v56, s90, v[2:3]
	v_ashrrev_i32_e32 v84, 5, v62
	v_add_co_u32_e32 v54, vcc, 0x1000, v54
	v_lshl_add_u64 v[56:57], v[56:57], 0, s[36:37]
	v_add_u32_e32 v62, s95, v84
	v_add_u32_e32 v66, 0x1e00, v96
	s_nop 0
	v_addc_co_u32_e32 v55, vcc, 0, v55, vcc
	v_lshl_add_u64 v[56:57], v[56:57], 0, v[128:129]
	v_mad_i64_i32 v[62:63], s[0:1], v62, s90, v[2:3]
	v_ashrrev_i32_e32 v85, 5, v66
	v_add_co_u32_e32 v58, vcc, 0x1000, v56
	v_lshl_add_u64 v[62:63], v[62:63], 0, s[36:37]
	v_add_u32_e32 v66, s95, v85
	s_nop 0
	v_addc_co_u32_e32 v59, vcc, 0, v57, vcc
	v_lshl_add_u64 v[62:63], v[62:63], 0, v[128:129]
	v_mad_i64_i32 v[2:3], s[0:1], v66, s90, v[2:3]
	v_add_co_u32_e32 v62, vcc, 0x1000, v62
	v_lshl_add_u64 v[2:3], v[2:3], 0, s[36:37]
	s_nop 0
	v_addc_co_u32_e32 v63, vcc, 0, v63, vcc
	v_lshl_add_u64 v[2:3], v[2:3], 0, v[128:129]
	v_add_co_u32_e32 v2, vcc, 0x1000, v2
	s_nop 0
	v_addc_co_u32_e32 v3, vcc, 0, v3, vcc
	v_lshl_add_u64 v[0:1], s[56:57], 0, v[0:1]
	v_lshlrev_b32_e32 v2, 4, v96
	v_and_b32_e32 v2, 0x1f0, v2
	v_add_u32_e32 v2, 0, v2
	v_mad_u64_u32 v[70:71], s[0:1], v103, s91, v[2:3]
	s_mov_b64 s[4:5], 0
	ds_write_b128 v70, v[184:187]
	v_mad_u64_u32 v[6:7], s[0:1], v5, s91, v[2:3]
	ds_write_b128 v6, v[188:191]
	v_mad_u64_u32 v[6:7], s[0:1], v72, s91, v[2:3]
	ds_write_b128 v6, v[192:195]
	v_mad_u64_u32 v[6:7], s[0:1], v73, s91, v[2:3]
	ds_write_b128 v6, v[196:199]
	v_mad_u64_u32 v[6:7], s[0:1], v74, s91, v[2:3]
	ds_write_b128 v6, v[200:203]
	v_mad_u64_u32 v[6:7], s[0:1], v75, s91, v[2:3]
	ds_write_b128 v6, v[204:207]
	v_mad_u64_u32 v[6:7], s[0:1], v76, s91, v[2:3]
	ds_write_b128 v6, v[208:211]
	v_mad_u64_u32 v[6:7], s[0:1], v77, s91, v[2:3]
	ds_write_b128 v6, v[212:215]
	v_mad_u64_u32 v[6:7], s[0:1], v78, s91, v[2:3]
	ds_write_b128 v6, v[216:219]
	v_mad_u64_u32 v[6:7], s[0:1], v79, s91, v[2:3]
	ds_write_b128 v6, v[220:223]
	v_mad_u64_u32 v[6:7], s[0:1], v80, s91, v[2:3]
	ds_write_b128 v6, v[224:227]
	v_mad_u64_u32 v[6:7], s[0:1], v81, s91, v[2:3]
	ds_write_b128 v6, v[228:231]
	v_mad_u64_u32 v[6:7], s[0:1], v82, s91, v[2:3]
	ds_write_b128 v6, v[232:235]
	v_mad_u64_u32 v[6:7], s[0:1], v83, s91, v[2:3]
	ds_write_b128 v6, v[236:239]
	v_mad_u64_u32 v[6:7], s[0:1], v84, s91, v[2:3]
	v_mad_u64_u32 v[2:3], s[0:1], v85, s91, v[2:3]
	ds_write_b128 v6, v[240:243]
	ds_write_b128 v2, v[244:247]
	s_waitcnt lgkmcnt(0)
	s_barrier
.LBB0_399:
	v_add_u32_e32 v2, 0xffffffa0, v4
	ds_read_b64_tr_b16 v[6:7], v2 offset:0
	ds_read_b64_tr_b16 v[8:9], v2 offset:0x840
	v_subrev_u32_e32 v2, 64, v4
	ds_read_b64_tr_b16 v[10:11], v2 offset:0
	ds_read_b64_tr_b16 v[12:13], v2 offset:0x840
	v_subrev_u32_e32 v2, 32, v4
	ds_read_b64_tr_b16 v[14:15], v2 offset:0
	ds_read_b64_tr_b16 v[16:17], v2 offset:0x840
	ds_read_b64_tr_b16 v[18:19], v4 offset:0
	ds_read_b64_tr_b16 v[20:21], v4 offset:0x840
	s_waitcnt lgkmcnt(0)
	v_lshl_add_u64 v[2:3], v[0:1], 0, s[4:5]
	s_mov_b32 s0, 0x6000000
	v_add_co_u32_e32 v22, vcc, s0, v2
	s_mov_b32 s1, 0x6002000
	s_nop 0
	v_addc_co_u32_e32 v23, vcc, 0, v3, vcc
	v_add_co_u32_e32 v24, vcc, s1, v2
	s_mov_b32 s2, 0x6004000
	s_nop 0
	v_addc_co_u32_e32 v25, vcc, 0, v3, vcc
	v_add_co_u32_e32 v26, vcc, s2, v2
	s_mov_b32 s3, 0x6006000
	s_add_u32 s4, s4, 0x8000
	v_addc_co_u32_e32 v27, vcc, 0, v3, vcc
	s_addc_u32 s5, s5, 0
	v_add_co_u32_e32 v2, vcc, s3, v2
	v_add_u32_e32 v4, 0x80, v4
	s_cmp_lg_u32 s4, 0x20000
	v_addc_co_u32_e32 v3, vcc, 0, v3, vcc
	global_store_dwordx4 v[22:23], v[6:9], off
	global_store_dwordx4 v[24:25], v[10:13], off
	global_store_dwordx4 v[26:27], v[14:17], off
	global_store_dwordx4 v[2:3], v[18:21], off
	s_cbranch_scc1 .LBB0_399
	v_mov_b32_e32 v1, v182
	v_mov_b32_e32 v0, v182
	v_mov_b32_e32 v14, v182
	s_waitcnt vmcnt(0)
	s_barrier
	s_add_u32 s8, s85, s6
	v_bfe_i32 v3, v14, 27, 1
	v_lshlrev_b32_e32 v2, 4, v14
	v_lshrrev_b32_e32 v3, 22, v3
	v_add_u32_e32 v3, v2, v3
	v_and_b32_e32 v3, 0xfffffc00, v3
	v_sub_u32_e32 v3, v2, v3
	v_ashrrev_i32_e32 v0, 31, v14
	v_lshrrev_b32_e32 v4, 4, v3
	v_lshrrev_b32_e32 v0, 26, v0
	v_bitop3_b32 v4, v4, v3, 32 bitop3:0x6c
	v_ashrrev_i32_e32 v3, 31, v3
	v_add_u32_e32 v0, v14, v0
	v_lshrrev_b32_e32 v3, 26, v3
	v_ashrrev_i32_e32 v0, 6, v0
	v_add_u32_e32 v3, v4, v3
	v_lshlrev_b32_e32 v5, 3, v0
	v_ashrrev_i32_e32 v3, 6, v3
	v_and_b32_e32 v5, -16, v5
	v_mul_i32_i24_e32 v6, 64, v3
	v_add_u32_e32 v5, v3, v5
	v_sub_u32_e32 v4, v4, v6
	v_lshlrev_b32_e32 v0, 5, v0
	v_ashrrev_i16_sdwa v4, v151, sext(v4) dst_sel:DWORD dst_unused:UNUSED_PAD src0_sel:DWORD src1_sel:BYTE_0
	v_lshlrev_b32_e32 v6, 1, v5
	v_lshrrev_b32_e32 v7, 2, v5
	v_and_b32_e32 v3, 3, v3
	v_and_b32_e32 v0, 32, v0
	v_bfe_i32 v4, v4, 0, 16
	v_and_b32_e32 v6, 24, v6
	v_and_b32_e32 v7, 4, v7
	v_and_or_b32 v3, v5, s92, v3
	v_or3_b32 v3, v3, v7, v6
	v_add_lshl_u32 v4, v0, v4, 1
	v_add_u32_e32 v2, 0x2000, v2
	v_lshl_add_u32 v128, v3, 9, v4
	v_ashrrev_i32_e32 v3, 31, v2
	v_lshrrev_b32_e32 v3, 22, v3
	v_add_u32_e32 v3, v2, v3
	v_ashrrev_i32_e32 v3, 10, v3
	v_lshl_add_u32 v0, v5, 9, v4
	v_mul_i32_i24_e32 v4, 0x400, v3
	v_sub_u32_e32 v2, v2, v4
	v_lshrrev_b32_e32 v4, 4, v2
	v_bitop3_b32 v2, v4, v2, 32 bitop3:0x6c
	v_ashrrev_i32_e32 v5, 31, v2
	v_lshrrev_b32_e32 v5, 26, v5
	s_addc_u32 s9, s86, s7
	v_readlane_b32 s0, v252, 27
	v_lshlrev_b32_e32 v4, 3, v3
	v_add_u32_e32 v5, v2, v5
	v_readlane_b32 s1, v252, 28
	s_add_u32 s4, s0, s6
	v_readfirstlane_b32 s0, v14
	v_and_b32_e32 v4, -16, v4
	v_ashrrev_i32_e32 v6, 6, v5
	v_and_b32_e32 v5, 0xc0, v5
	s_addc_u32 s5, s1, s7
	v_add_u32_e32 v4, v6, v4
	v_sub_u32_e32 v2, v2, v5
	s_ashr_i32 s3, s0, 6
	v_lshlrev_b32_e32 v3, 5, v3
	v_ashrrev_i16_sdwa v2, v151, sext(v2) dst_sel:DWORD dst_unused:UNUSED_PAD src0_sel:DWORD src1_sel:BYTE_0
	v_lshlrev_b32_e32 v5, 1, v4
	v_lshrrev_b32_e32 v7, 2, v4
	v_and_b32_e32 v6, 3, v6
	s_lshl_b32 s33, s3, 10
	v_and_b32_e32 v3, 32, v3
	v_bfe_i32 v2, v2, 0, 16
	v_and_b32_e32 v5, 24, v5
	v_and_b32_e32 v7, 4, v7
	v_and_or_b32 v6, v4, s92, v6
	s_add_i32 s41, s33, 0
	v_or3_b32 v5, v6, v7, v5
	v_add_lshl_u32 v3, v3, v2, 1
	s_add_i32 m0, s41, 0x10000
	v_lshl_add_u32 v2, v4, 9, v3
	v_lshl_add_u32 v4, v5, 9, v3
	global_load_lds_dwordx4 v128, s[4:5]
	s_add_i32 m0, s41, 0x12000
	s_ashr_i32 s2, s0, 8
	global_load_lds_dwordx4 v4, s[4:5]
	s_mov_b32 m0, s41
	s_add_i32 s42, s41, 0x2000
	global_load_lds_dwordx4 v0, s[8:9]
	s_mov_b32 m0, s42
	s_add_u32 s6, s4, 0x10000
	global_load_lds_dwordx4 v2, s[8:9]
	s_addc_u32 s7, s5, 0
	s_add_i32 m0, s41, 0x14000
	v_readfirstlane_b32 s1, v1
	global_load_lds_dwordx4 v128, s[6:7]
	s_add_i32 m0, s41, 0x16000
	v_mov_b32_e32 v5, v129
	global_load_lds_dwordx4 v4, s[6:7]
	s_add_u32 s6, s8, 0x10000
	s_addc_u32 s7, s9, 0
	s_add_i32 s40, s41, 0x4000
	s_mov_b32 m0, s40
	s_add_i32 s18, s41, 0x6000
	global_load_lds_dwordx4 v0, s[6:7]
	s_mov_b32 m0, s18
	v_mov_b32_e32 v1, v129
	global_load_lds_dwordx4 v2, s[6:7]
	v_mov_b32_e32 v3, v129
	v_lshl_add_u64 v[12:13], s[4:5], 0, v[128:129]
	v_lshl_add_u64 v[10:11], s[4:5], 0, v[4:5]
	v_lshl_add_u64 v[6:7], s[8:9], 0, v[0:1]
	s_cmp_lg_u32 s2, 1
	v_lshl_add_u64 v[8:9], s[8:9], 0, v[2:3]
	s_cbranch_scc1 .LBB0_402
	s_barrier
	s_branch .Lpadskip_1
	s_nop 0
	s_nop 0
	s_nop 0
	s_nop 0
	s_nop 0
	s_nop 0
	s_nop 0
	s_nop 0
	s_nop 0
	s_nop 0
	s_nop 0
	s_nop 0
	s_nop 0
	s_nop 0
	s_nop 0
	s_nop 0
	s_nop 0
	s_nop 0
.Lpadskip_1:
.LBB0_402:
	s_add_i32 s36, s93, s33
	s_lshl_b32 s3, s3, 12
	v_lshl_add_u64 v[16:17], v[12:13], 0, s[70:71]
	s_mov_b32 m0, s36
	s_add_i32 s19, s36, 0x2000
	s_lshl_b32 s10, s2, 13
	s_and_b32 s11, s3, 0x3000
	s_waitcnt vmcnt(4)
	s_barrier
	global_load_lds_dwordx4 v[16:17], off
	v_lshl_add_u64 v[16:17], v[10:11], 0, s[70:71]
	s_mov_b32 m0, s19
	s_add_i32 s16, s41, 0x8000
	s_add_i32 s15, s41, 0xa000
	global_load_lds_dwordx4 v[16:17], off
	v_lshl_add_u64 v[16:17], v[6:7], 0, s[70:71]
	s_mov_b32 m0, s16
	s_add_u32 s6, s4, 0x10080
	global_load_lds_dwordx4 v[16:17], off
	v_lshl_add_u64 v[16:17], v[8:9], 0, s[70:71]
	s_mov_b32 m0, s15
	s_addc_u32 s7, s5, 0
	s_add_i32 s2, s94, s33
	global_load_lds_dwordx4 v[16:17], off
	v_lshl_add_u64 v[16:17], s[6:7], 0, v[128:129]
	s_mov_b32 m0, s2
	s_add_i32 s3, s2, 0x2000
	global_load_lds_dwordx4 v[16:17], off
	v_lshl_add_u64 v[16:17], s[6:7], 0, v[4:5]
	s_mov_b32 m0, s3
	v_and_b32_e32 v15, 15, v14
	global_load_lds_dwordx4 v[16:17], off
	v_and_b32_e32 v16, 48, v14
	v_lshlrev_b32_e32 v14, 2, v14
	v_lshlrev_b32_e32 v15, 6, v15
	v_and_b32_e32 v14, 32, v14
	v_or_b32_e32 v17, v15, v16
	v_bitop3_b32 v15, v15, v14, v16 bitop3:0x36
	v_or_b32_e32 v64, s11, v15
	s_add_i32 s43, 0, 0x10000
	v_bitop3_b32 v14, v17, s10, v14 bitop3:0xde
	v_add_u32_e32 v131, s43, v64
	s_waitcnt vmcnt(6)
	s_barrier
	s_add_u32 s48, s8, 0x10080
	v_add_u32_e32 v183, 0, v14
	ds_read_b128 v[14:17], v131
	ds_read_b128 v[18:21], v131 offset:1024
	ds_read_b128 v[22:25], v131 offset:2048
	ds_read_b128 v[26:29], v131 offset:3072
	s_addc_u32 s49, s9, 0
	s_add_i32 s50, 0, 0x14000
	s_add_u32 s12, s4, 0x10100
	s_addc_u32 s13, s5, 0
	s_add_u32 s10, s8, 0x10100
	s_addc_u32 s11, s9, 0
	s_add_u32 s6, s4, 0x10180
	v_add_u32_e32 v144, s50, v64
	s_addc_u32 s7, s5, 0
	s_add_i32 s17, s41, 0xc000
	v_lshl_add_u64 v[62:63], s[48:49], 0, v[0:1]
	s_mov_b32 m0, s17
	s_add_i32 s14, s41, 0xe000
	ds_read_b128 v[30:33], v183
	ds_read_b128 v[34:37], v183 offset:1024
	ds_read_b128 v[38:41], v183 offset:2048
	ds_read_b128 v[42:45], v183 offset:3072
	ds_read_b128 v[46:49], v183 offset:4096
	ds_read_b128 v[50:53], v183 offset:5120
	ds_read_b128 v[54:57], v183 offset:6144
	ds_read_b128 v[58:61], v183 offset:7168
	global_load_lds_dwordx4 v[62:63], off
	v_lshl_add_u64 v[62:63], s[48:49], 0, v[2:3]
	s_mov_b32 m0, s14
	v_add_u32_e32 v145, s93, v64
	global_load_lds_dwordx4 v[62:63], off
	s_waitcnt lgkmcnt(8)
	s_barrier
	s_waitcnt lgkmcnt(0)
	v_add_u32_e32 v146, s94, v64
	s_setprio 1
	s_waitcnt lgkmcnt(0)
	v_mfma_f32_16x16x32_bf16 v[62:65], v[14:17], v[30:33], 0
	v_mfma_f32_16x16x32_bf16 v[66:69], v[22:25], v[30:33], 0
	v_mfma_f32_16x16x32_bf16 v[70:73], v[14:17], v[38:41], 0
	v_mfma_f32_16x16x32_bf16 v[74:77], v[22:25], v[38:41], 0
	v_mfma_f32_16x16x32_bf16 v[78:81], v[14:17], v[46:49], 0
	v_mfma_f32_16x16x32_bf16 v[82:85], v[22:25], v[46:49], 0
	v_mfma_f32_16x16x32_bf16 v[86:89], v[14:17], v[54:57], 0
	v_mfma_f32_16x16x32_bf16 v[90:93], v[22:25], v[54:57], 0
	v_mfma_f32_16x16x32_bf16 v[62:65], v[18:21], v[34:37], v[62:65]
	v_mfma_f32_16x16x32_bf16 v[66:69], v[26:29], v[34:37], v[66:69]
	v_mfma_f32_16x16x32_bf16 v[70:73], v[18:21], v[42:45], v[70:73]
	v_mfma_f32_16x16x32_bf16 v[74:77], v[26:29], v[42:45], v[74:77]
	v_mfma_f32_16x16x32_bf16 v[78:81], v[18:21], v[50:53], v[78:81]
	v_mfma_f32_16x16x32_bf16 v[82:85], v[26:29], v[50:53], v[82:85]
	v_mfma_f32_16x16x32_bf16 v[86:89], v[18:21], v[58:61], v[86:89]
	v_mfma_f32_16x16x32_bf16 v[90:93], v[26:29], v[58:61], v[90:93]
	s_setprio 0
	s_barrier
	s_add_i32 s43, s43, s33
	v_lshl_add_u64 v[110:111], v[12:13], 0, s[72:73]
	s_mov_b32 m0, s43
	ds_read_b128 v[94:97], v144
	ds_read_b128 v[98:101], v144 offset:1024
	ds_read_b128 v[102:105], v144 offset:2048
	ds_read_b128 v[106:109], v144 offset:3072
	global_load_lds_dwordx4 v[110:111], off
	v_lshl_add_u64 v[110:111], v[10:11], 0, s[72:73]
	s_add_i32 m0, s43, 0x2000
	s_nop 0
	global_load_lds_dwordx4 v[110:111], off
	s_barrier
	s_waitcnt lgkmcnt(0)
	s_setprio 1
	s_waitcnt lgkmcnt(0)
	v_mfma_f32_16x16x32_bf16 v[110:113], v[94:97], v[30:33], 0
	v_mfma_f32_16x16x32_bf16 v[30:33], v[102:105], v[30:33], 0
	v_mfma_f32_16x16x32_bf16 v[110:113], v[98:101], v[34:37], v[110:113]
	v_mfma_f32_16x16x32_bf16 v[30:33], v[106:109], v[34:37], v[30:33]
	v_mfma_f32_16x16x32_bf16 v[34:37], v[94:97], v[38:41], 0
	v_mfma_f32_16x16x32_bf16 v[38:41], v[102:105], v[38:41], 0
	v_mfma_f32_16x16x32_bf16 v[34:37], v[98:101], v[42:45], v[34:37]
	v_mfma_f32_16x16x32_bf16 v[38:41], v[106:109], v[42:45], v[38:41]
	v_mfma_f32_16x16x32_bf16 v[42:45], v[94:97], v[46:49], 0
	v_mfma_f32_16x16x32_bf16 v[46:49], v[102:105], v[46:49], 0
	v_mfma_f32_16x16x32_bf16 v[42:45], v[98:101], v[50:53], v[42:45]
	v_mfma_f32_16x16x32_bf16 v[46:49], v[106:109], v[50:53], v[46:49]
	v_mfma_f32_16x16x32_bf16 v[50:53], v[94:97], v[54:57], 0
	v_mfma_f32_16x16x32_bf16 v[54:57], v[102:105], v[54:57], 0
	v_mfma_f32_16x16x32_bf16 v[50:53], v[98:101], v[58:61], v[50:53]
	v_mfma_f32_16x16x32_bf16 v[54:57], v[106:109], v[58:61], v[54:57]
	s_setprio 0
	s_mov_b32 m0, s41
	v_lshl_add_u64 v[126:127], v[6:7], 0, s[72:73]
	s_barrier
	ds_read_b128 v[58:61], v183 offset:16384
	ds_read_b128 v[114:117], v183 offset:17408
	ds_read_b128 v[118:121], v183 offset:18432
	ds_read_b128 v[122:125], v183 offset:19456
	ds_read_b128 v[132:135], v183 offset:20480
	ds_read_b128 v[136:139], v183 offset:21504
	ds_read_b128 v[140:143], v183 offset:22528
	ds_read_b128 v[152:155], v183 offset:23552
	global_load_lds_dwordx4 v[126:127], off
	v_lshl_add_u64 v[126:127], v[8:9], 0, s[72:73]
	s_mov_b32 m0, s42
	s_nop 0
	global_load_lds_dwordx4 v[126:127], off
	s_barrier
	s_waitcnt lgkmcnt(0)
	s_setprio 1
	s_waitcnt lgkmcnt(0)
	v_mfma_f32_16x16x32_bf16 v[156:159], v[14:17], v[58:61], 0
	v_mfma_f32_16x16x32_bf16 v[164:167], v[14:17], v[118:121], 0
	v_mfma_f32_16x16x32_bf16 v[172:175], v[14:17], v[132:135], 0
	v_mfma_f32_16x16x32_bf16 v[14:17], v[14:17], v[140:143], 0
	v_mfma_f32_16x16x32_bf16 v[156:159], v[18:21], v[114:117], v[156:159]
	v_mfma_f32_16x16x32_bf16 v[164:167], v[18:21], v[122:125], v[164:167]
	v_mfma_f32_16x16x32_bf16 v[172:175], v[18:21], v[136:139], v[172:175]
	v_mfma_f32_16x16x32_bf16 v[14:17], v[18:21], v[152:155], v[14:17]
	v_mfma_f32_16x16x32_bf16 v[18:21], v[22:25], v[140:143], 0
	v_mfma_f32_16x16x32_bf16 v[160:163], v[22:25], v[58:61], 0
	v_mfma_f32_16x16x32_bf16 v[168:171], v[22:25], v[118:121], 0
	v_mfma_f32_16x16x32_bf16 v[176:179], v[22:25], v[132:135], 0
	v_mfma_f32_16x16x32_bf16 v[18:21], v[26:29], v[152:155], v[18:21]
	v_mfma_f32_16x16x32_bf16 v[160:163], v[26:29], v[114:117], v[160:163]
	v_mfma_f32_16x16x32_bf16 v[168:171], v[26:29], v[122:125], v[168:171]
	v_mfma_f32_16x16x32_bf16 v[176:179], v[26:29], v[136:139], v[176:179]
	s_setprio 0
	s_barrier
	s_add_i32 s33, s50, s33
	v_lshl_add_u64 v[22:23], s[12:13], 0, v[128:129]
	s_mov_b32 m0, s33
	s_nop 0
	global_load_lds_dwordx4 v[22:23], off
	v_lshl_add_u64 v[22:23], s[12:13], 0, v[4:5]
	s_add_i32 m0, s33, 0x2000
	s_nop 0
	global_load_lds_dwordx4 v[22:23], off
	s_waitcnt vmcnt(6)
	s_barrier
	s_setprio 1
	v_mfma_f32_16x16x32_bf16 v[22:25], v[94:97], v[58:61], 0
	v_mfma_f32_16x16x32_bf16 v[26:29], v[102:105], v[58:61], 0
	v_mfma_f32_16x16x32_bf16 v[22:25], v[98:101], v[114:117], v[22:25]
	v_mfma_f32_16x16x32_bf16 v[26:29], v[106:109], v[114:117], v[26:29]
	v_mfma_f32_16x16x32_bf16 v[58:61], v[94:97], v[118:121], 0
	v_mfma_f32_16x16x32_bf16 v[114:117], v[102:105], v[118:121], 0
	v_mfma_f32_16x16x32_bf16 v[118:121], v[94:97], v[132:135], 0
	v_mfma_f32_16x16x32_bf16 v[94:97], v[94:97], v[140:143], 0
	v_mfma_f32_16x16x32_bf16 v[58:61], v[98:101], v[122:125], v[58:61]
	v_mfma_f32_16x16x32_bf16 v[114:117], v[106:109], v[122:125], v[114:117]
	v_mfma_f32_16x16x32_bf16 v[118:121], v[98:101], v[136:139], v[118:121]
	v_mfma_f32_16x16x32_bf16 v[122:125], v[102:105], v[132:135], 0
	v_mfma_f32_16x16x32_bf16 v[94:97], v[98:101], v[152:155], v[94:97]
	v_mfma_f32_16x16x32_bf16 v[98:101], v[102:105], v[140:143], 0
	v_mfma_f32_16x16x32_bf16 v[122:125], v[106:109], v[136:139], v[122:125]
	v_mfma_f32_16x16x32_bf16 v[98:101], v[106:109], v[152:155], v[98:101]
	s_setprio 0
	s_barrier
	ds_read_b128 v[102:105], v145
	ds_read_b128 v[106:109], v145 offset:1024
	ds_read_b128 v[132:135], v145 offset:2048
	ds_read_b128 v[136:139], v145 offset:3072
	s_mov_b32 m0, s40
	v_lshl_add_u64 v[126:127], s[10:11], 0, v[0:1]
	ds_read_b128 v[140:143], v183 offset:32768
	ds_read_b128 v[152:155], v183 offset:33792
	ds_read_b128 v[184:187], v183 offset:34816
	ds_read_b128 v[188:191], v183 offset:35840
	ds_read_b128 v[192:195], v183 offset:36864
	ds_read_b128 v[196:199], v183 offset:37888
	ds_read_b128 v[200:203], v183 offset:38912
	ds_read_b128 v[204:207], v183 offset:39936
	global_load_lds_dwordx4 v[126:127], off
	v_lshl_add_u64 v[126:127], s[10:11], 0, v[2:3]
	s_mov_b32 m0, s18
	s_nop 0
	global_load_lds_dwordx4 v[126:127], off
	s_waitcnt lgkmcnt(8)
	s_barrier
	s_waitcnt lgkmcnt(0)
	s_setprio 1
	s_waitcnt lgkmcnt(0)
	v_mfma_f32_16x16x32_bf16 v[62:65], v[102:105], v[140:143], v[62:65]
	v_mfma_f32_16x16x32_bf16 v[66:69], v[132:135], v[140:143], v[66:69]
	v_mfma_f32_16x16x32_bf16 v[70:73], v[102:105], v[184:187], v[70:73]
	v_mfma_f32_16x16x32_bf16 v[74:77], v[132:135], v[184:187], v[74:77]
	v_mfma_f32_16x16x32_bf16 v[78:81], v[102:105], v[192:195], v[78:81]
	v_mfma_f32_16x16x32_bf16 v[82:85], v[132:135], v[192:195], v[82:85]
	v_mfma_f32_16x16x32_bf16 v[86:89], v[102:105], v[200:203], v[86:89]
	v_mfma_f32_16x16x32_bf16 v[90:93], v[132:135], v[200:203], v[90:93]
	v_mfma_f32_16x16x32_bf16 v[62:65], v[106:109], v[152:155], v[62:65]
	v_mfma_f32_16x16x32_bf16 v[66:69], v[136:139], v[152:155], v[66:69]
	v_mfma_f32_16x16x32_bf16 v[70:73], v[106:109], v[188:191], v[70:73]
	v_mfma_f32_16x16x32_bf16 v[74:77], v[136:139], v[188:191], v[74:77]
	v_mfma_f32_16x16x32_bf16 v[78:81], v[106:109], v[196:199], v[78:81]
	v_mfma_f32_16x16x32_bf16 v[82:85], v[136:139], v[196:199], v[82:85]
	v_mfma_f32_16x16x32_bf16 v[86:89], v[106:109], v[204:207], v[86:89]
	v_mfma_f32_16x16x32_bf16 v[90:93], v[136:139], v[204:207], v[90:93]
	s_setprio 0
	s_barrier
	s_mov_b32 m0, s36
	v_lshl_add_u64 v[12:13], v[12:13], 0, s[76:77]
	ds_read_b128 v[208:211], v146
	ds_read_b128 v[212:215], v146 offset:1024
	ds_read_b128 v[216:219], v146 offset:2048
	ds_read_b128 v[220:223], v146 offset:3072
	global_load_lds_dwordx4 v[12:13], off
	v_lshl_add_u64 v[10:11], v[10:11], 0, s[76:77]
	s_mov_b32 m0, s19
	s_nop 0
	global_load_lds_dwordx4 v[10:11], off
	s_barrier
	s_waitcnt lgkmcnt(0)
	s_setprio 1
	s_waitcnt lgkmcnt(0)
	v_mfma_f32_16x16x32_bf16 v[10:13], v[208:211], v[140:143], v[110:113]
	v_mfma_f32_16x16x32_bf16 v[30:33], v[216:219], v[140:143], v[30:33]
	v_mfma_f32_16x16x32_bf16 v[34:37], v[208:211], v[184:187], v[34:37]
	v_mfma_f32_16x16x32_bf16 v[38:41], v[216:219], v[184:187], v[38:41]
	v_mfma_f32_16x16x32_bf16 v[42:45], v[208:211], v[192:195], v[42:45]
	v_mfma_f32_16x16x32_bf16 v[46:49], v[216:219], v[192:195], v[46:49]
	v_mfma_f32_16x16x32_bf16 v[50:53], v[208:211], v[200:203], v[50:53]
	v_mfma_f32_16x16x32_bf16 v[54:57], v[216:219], v[200:203], v[54:57]
	v_mfma_f32_16x16x32_bf16 v[10:13], v[212:215], v[152:155], v[10:13]
	v_mfma_f32_16x16x32_bf16 v[30:33], v[220:223], v[152:155], v[30:33]
	v_mfma_f32_16x16x32_bf16 v[34:37], v[212:215], v[188:191], v[34:37]
	v_mfma_f32_16x16x32_bf16 v[38:41], v[220:223], v[188:191], v[38:41]
	v_mfma_f32_16x16x32_bf16 v[42:45], v[212:215], v[196:199], v[42:45]
	v_mfma_f32_16x16x32_bf16 v[46:49], v[220:223], v[196:199], v[46:49]
	v_mfma_f32_16x16x32_bf16 v[50:53], v[212:215], v[204:207], v[50:53]
	v_mfma_f32_16x16x32_bf16 v[54:57], v[220:223], v[204:207], v[54:57]
	s_setprio 0
	s_mov_b32 m0, s16
	v_lshl_add_u64 v[6:7], v[6:7], 0, s[76:77]
	s_barrier
	ds_read_b128 v[110:113], v183 offset:49152
	ds_read_b128 v[140:143], v183 offset:50176
	ds_read_b128 v[152:155], v183 offset:51200
	ds_read_b128 v[184:187], v183 offset:52224
	ds_read_b128 v[188:191], v183 offset:53248
	ds_read_b128 v[192:195], v183 offset:54272
	ds_read_b128 v[196:199], v183 offset:55296
	ds_read_b128 v[200:203], v183 offset:56320
	global_load_lds_dwordx4 v[6:7], off
	v_lshl_add_u64 v[6:7], v[8:9], 0, s[76:77]
	s_mov_b32 m0, s15
	s_nop 0
	global_load_lds_dwordx4 v[6:7], off
	s_barrier
	s_waitcnt lgkmcnt(0)
	s_setprio 1
	s_waitcnt lgkmcnt(0)
	v_mfma_f32_16x16x32_bf16 v[6:9], v[102:105], v[110:113], v[156:159]
	v_mfma_f32_16x16x32_bf16 v[14:17], v[102:105], v[196:199], v[14:17]
	v_mfma_f32_16x16x32_bf16 v[18:21], v[132:135], v[196:199], v[18:21]
	v_mfma_f32_16x16x32_bf16 v[6:9], v[106:109], v[140:143], v[6:9]
	v_mfma_f32_16x16x32_bf16 v[156:159], v[132:135], v[110:113], v[160:163]
	v_mfma_f32_16x16x32_bf16 v[160:163], v[102:105], v[152:155], v[164:167]
	v_mfma_f32_16x16x32_bf16 v[164:167], v[132:135], v[152:155], v[168:171]
	v_mfma_f32_16x16x32_bf16 v[168:171], v[102:105], v[188:191], v[172:175]
	v_mfma_f32_16x16x32_bf16 v[172:175], v[132:135], v[188:191], v[176:179]
	v_mfma_f32_16x16x32_bf16 v[14:17], v[106:109], v[200:203], v[14:17]
	v_mfma_f32_16x16x32_bf16 v[18:21], v[136:139], v[200:203], v[18:21]
	v_mfma_f32_16x16x32_bf16 v[156:159], v[136:139], v[140:143], v[156:159]
	v_mfma_f32_16x16x32_bf16 v[160:163], v[106:109], v[184:187], v[160:163]
	v_mfma_f32_16x16x32_bf16 v[164:167], v[136:139], v[184:187], v[164:167]
	v_mfma_f32_16x16x32_bf16 v[168:171], v[106:109], v[192:195], v[168:171]
	v_mfma_f32_16x16x32_bf16 v[172:175], v[136:139], v[192:195], v[172:175]
	s_setprio 0
	s_barrier
	s_mov_b32 m0, s2
	v_lshl_add_u64 v[102:103], s[6:7], 0, v[128:129]
	global_load_lds_dwordx4 v[102:103], off
	v_lshl_add_u64 v[4:5], s[6:7], 0, v[4:5]
	s_mov_b32 m0, s3
	s_nop 0
	global_load_lds_dwordx4 v[4:5], off
	s_waitcnt vmcnt(6)
	s_barrier
	s_setprio 1
	v_mfma_f32_16x16x32_bf16 v[22:25], v[208:211], v[110:113], v[22:25]
	v_mfma_f32_16x16x32_bf16 v[26:29], v[216:219], v[110:113], v[26:29]
	v_mfma_f32_16x16x32_bf16 v[58:61], v[208:211], v[152:155], v[58:61]
	v_mfma_f32_16x16x32_bf16 v[102:105], v[216:219], v[152:155], v[114:117]
	v_mfma_f32_16x16x32_bf16 v[106:109], v[208:211], v[188:191], v[118:121]
	v_mfma_f32_16x16x32_bf16 v[110:113], v[216:219], v[188:191], v[122:125]
	v_mfma_f32_16x16x32_bf16 v[94:97], v[208:211], v[196:199], v[94:97]
	v_mfma_f32_16x16x32_bf16 v[98:101], v[216:219], v[196:199], v[98:101]
	v_mfma_f32_16x16x32_bf16 v[22:25], v[212:215], v[140:143], v[22:25]
	v_mfma_f32_16x16x32_bf16 v[26:29], v[220:223], v[140:143], v[26:29]
	v_mfma_f32_16x16x32_bf16 v[58:61], v[212:215], v[184:187], v[58:61]
	v_mfma_f32_16x16x32_bf16 v[102:105], v[220:223], v[184:187], v[102:105]
	v_mfma_f32_16x16x32_bf16 v[106:109], v[212:215], v[192:195], v[106:109]
	v_mfma_f32_16x16x32_bf16 v[110:113], v[220:223], v[192:195], v[110:113]
	v_mfma_f32_16x16x32_bf16 v[94:97], v[212:215], v[200:203], v[94:97]
	v_mfma_f32_16x16x32_bf16 v[98:101], v[220:223], v[200:203], v[98:101]
	s_setprio 0
	s_add_u32 s2, s8, 0x10180
	s_addc_u32 s3, s9, 0
	s_mov_b32 m0, s17
	v_lshl_add_u64 v[0:1], s[2:3], 0, v[0:1]
	s_barrier
	ds_read_b128 v[114:117], v131
	ds_read_b128 v[118:121], v131 offset:1024
	ds_read_b128 v[122:125], v131 offset:2048
	ds_read_b128 v[132:135], v131 offset:3072
	ds_read_b128 v[136:139], v183
	ds_read_b128 v[140:143], v183 offset:1024
	ds_read_b128 v[152:155], v183 offset:2048
	ds_read_b128 v[176:179], v183 offset:3072
	ds_read_b128 v[184:187], v183 offset:4096
	ds_read_b128 v[188:191], v183 offset:5120
	ds_read_b128 v[192:195], v183 offset:6144
	ds_read_b128 v[196:199], v183 offset:7168
	global_load_lds_dwordx4 v[0:1], off
	v_lshl_add_u64 v[0:1], s[2:3], 0, v[2:3]
	s_mov_b32 m0, s14
	s_nop 0
	global_load_lds_dwordx4 v[0:1], off
	s_barrier
	s_waitcnt lgkmcnt(0)
	s_setprio 1
	s_waitcnt lgkmcnt(0)
	v_mfma_f32_16x16x32_bf16 v[0:3], v[114:117], v[136:139], v[62:65]
	v_mfma_f32_16x16x32_bf16 v[62:65], v[122:125], v[136:139], v[66:69]
	v_mfma_f32_16x16x32_bf16 v[66:69], v[114:117], v[152:155], v[70:73]
	v_mfma_f32_16x16x32_bf16 v[70:73], v[122:125], v[152:155], v[74:77]
	v_mfma_f32_16x16x32_bf16 v[74:77], v[114:117], v[184:187], v[78:81]
	v_mfma_f32_16x16x32_bf16 v[78:81], v[122:125], v[184:187], v[82:85]
	v_mfma_f32_16x16x32_bf16 v[82:85], v[114:117], v[192:195], v[86:89]
	v_mfma_f32_16x16x32_bf16 v[0:3], v[118:121], v[140:143], v[0:3]
	v_mfma_f32_16x16x32_bf16 v[62:65], v[132:135], v[140:143], v[62:65]
	v_mfma_f32_16x16x32_bf16 v[66:69], v[118:121], v[176:179], v[66:69]
	v_mfma_f32_16x16x32_bf16 v[70:73], v[132:135], v[176:179], v[70:73]
	v_mfma_f32_16x16x32_bf16 v[74:77], v[118:121], v[188:191], v[74:77]
	v_mfma_f32_16x16x32_bf16 v[78:81], v[132:135], v[188:191], v[78:81]
	v_mfma_f32_16x16x32_bf16 v[82:85], v[118:121], v[196:199], v[82:85]
	v_mfma_f32_16x16x32_bf16 v[86:89], v[122:125], v[192:195], v[90:93]
	v_mfma_f32_16x16x32_bf16 v[200:203], v[132:135], v[196:199], v[86:89]
	s_setprio 0
	s_barrier
	s_nop 4
	ds_read_b128 v[86:89], v144
	ds_read_b128 v[90:93], v144 offset:1024
	ds_read_b128 v[204:207], v144 offset:2048
	ds_read_b128 v[208:211], v144 offset:3072
	s_barrier
	s_waitcnt lgkmcnt(0)
	s_setprio 1
	s_waitcnt lgkmcnt(0)
	v_mfma_f32_16x16x32_bf16 v[30:33], v[204:207], v[136:139], v[30:33]
	v_mfma_f32_16x16x32_bf16 v[10:13], v[86:89], v[136:139], v[10:13]
	v_mfma_f32_16x16x32_bf16 v[136:139], v[208:211], v[140:143], v[30:33]
	v_mfma_f32_16x16x32_bf16 v[30:33], v[86:89], v[152:155], v[34:37]
	v_mfma_f32_16x16x32_bf16 v[10:13], v[90:93], v[140:143], v[10:13]
	v_mfma_f32_16x16x32_bf16 v[140:143], v[90:93], v[176:179], v[30:33]
	v_mfma_f32_16x16x32_bf16 v[30:33], v[204:207], v[152:155], v[38:41]
	v_mfma_f32_16x16x32_bf16 v[152:155], v[208:211], v[176:179], v[30:33]
	v_mfma_f32_16x16x32_bf16 v[30:33], v[86:89], v[184:187], v[42:45]
	v_mfma_f32_16x16x32_bf16 v[40:43], v[90:93], v[188:191], v[30:33]
	v_mfma_f32_16x16x32_bf16 v[30:33], v[204:207], v[184:187], v[46:49]
	v_mfma_f32_16x16x32_bf16 v[44:47], v[208:211], v[188:191], v[30:33]
	v_mfma_f32_16x16x32_bf16 v[30:33], v[86:89], v[192:195], v[50:53]
	v_mfma_f32_16x16x32_bf16 v[48:51], v[90:93], v[196:199], v[30:33]
	v_mfma_f32_16x16x32_bf16 v[30:33], v[204:207], v[192:195], v[54:57]
	v_mfma_f32_16x16x32_bf16 v[52:55], v[208:211], v[196:199], v[30:33]
	s_setprio 0
	s_barrier
	s_nop 4
	ds_read_b128 v[30:33], v183 offset:16384
	ds_read_b128 v[34:37], v183 offset:17408
	ds_read_b128 v[176:179], v183 offset:18432
	ds_read_b128 v[184:187], v183 offset:19456
	ds_read_b128 v[188:191], v183 offset:20480
	ds_read_b128 v[192:195], v183 offset:21504
	ds_read_b128 v[196:199], v183 offset:22528
	ds_read_b128 v[212:215], v183 offset:23552
	s_waitcnt vmcnt(4)
	s_barrier
	s_waitcnt lgkmcnt(0)
	s_setprio 1
	s_waitcnt lgkmcnt(0)
	v_mfma_f32_16x16x32_bf16 v[4:7], v[114:117], v[30:33], v[6:9]
	v_mfma_f32_16x16x32_bf16 v[14:17], v[114:117], v[196:199], v[14:17]
	v_mfma_f32_16x16x32_bf16 v[4:7], v[118:121], v[34:37], v[4:7]
	v_mfma_f32_16x16x32_bf16 v[156:159], v[122:125], v[30:33], v[156:159]
	v_mfma_f32_16x16x32_bf16 v[160:163], v[114:117], v[176:179], v[160:163]
	v_mfma_f32_16x16x32_bf16 v[164:167], v[122:125], v[176:179], v[164:167]
	v_mfma_f32_16x16x32_bf16 v[168:171], v[114:117], v[188:191], v[168:171]
	v_mfma_f32_16x16x32_bf16 v[172:175], v[122:125], v[188:191], v[172:175]
	v_mfma_f32_16x16x32_bf16 v[216:219], v[118:121], v[212:215], v[14:17]
	v_mfma_f32_16x16x32_bf16 v[14:17], v[122:125], v[196:199], v[18:21]
	v_mfma_f32_16x16x32_bf16 v[156:159], v[132:135], v[34:37], v[156:159]
	v_mfma_f32_16x16x32_bf16 v[160:163], v[118:121], v[184:187], v[160:163]
	v_mfma_f32_16x16x32_bf16 v[164:167], v[132:135], v[184:187], v[164:167]
	v_mfma_f32_16x16x32_bf16 v[168:171], v[118:121], v[192:195], v[168:171]
	v_mfma_f32_16x16x32_bf16 v[172:175], v[132:135], v[192:195], v[172:175]
	v_mfma_f32_16x16x32_bf16 v[132:135], v[132:135], v[212:215], v[14:17]
	s_setprio 0
	s_setprio 1
	v_mfma_f32_16x16x32_bf16 v[14:17], v[86:89], v[30:33], v[22:25]
	v_mfma_f32_16x16x32_bf16 v[220:223], v[90:93], v[34:37], v[14:17]
	v_mfma_f32_16x16x32_bf16 v[14:17], v[204:207], v[30:33], v[26:29]
	v_mfma_f32_16x16x32_bf16 v[24:27], v[208:211], v[34:37], v[14:17]
	v_mfma_f32_16x16x32_bf16 v[14:17], v[86:89], v[176:179], v[58:61]
	v_mfma_f32_16x16x32_bf16 v[28:31], v[90:93], v[184:187], v[14:17]
	v_mfma_f32_16x16x32_bf16 v[14:17], v[204:207], v[176:179], v[102:105]
	v_mfma_f32_16x16x32_bf16 v[176:179], v[208:211], v[184:187], v[14:17]
	v_mfma_f32_16x16x32_bf16 v[14:17], v[86:89], v[188:191], v[106:109]
	v_mfma_f32_16x16x32_bf16 v[184:187], v[90:93], v[192:195], v[14:17]
	v_mfma_f32_16x16x32_bf16 v[14:17], v[204:207], v[188:191], v[110:113]
	v_mfma_f32_16x16x32_bf16 v[188:191], v[208:211], v[192:195], v[14:17]
	v_mfma_f32_16x16x32_bf16 v[14:17], v[86:89], v[196:199], v[94:97]
	v_mfma_f32_16x16x32_bf16 v[192:195], v[90:93], v[212:215], v[14:17]
	v_mfma_f32_16x16x32_bf16 v[14:17], v[204:207], v[196:199], v[98:101]
	v_mfma_f32_16x16x32_bf16 v[196:199], v[208:211], v[212:215], v[14:17]
	s_setprio 0
	s_barrier
	ds_read_b128 v[204:207], v145
	ds_read_b128 v[208:211], v145 offset:1024
	ds_read_b128 v[212:215], v145 offset:2048
	ds_read_b128 v[224:227], v145 offset:3072
	s_nop 0
	ds_read_b128 v[14:17], v183 offset:32768
	ds_read_b128 v[18:21], v183 offset:33792
	ds_read_b128 v[96:99], v183 offset:34816
	ds_read_b128 v[100:103], v183 offset:35840
	ds_read_b128 v[228:231], v183 offset:36864
	ds_read_b128 v[232:235], v183 offset:37888
	ds_read_b128 v[236:239], v183 offset:38912
	ds_read_b128 v[240:243], v183 offset:39936
	s_waitcnt vmcnt(2)
	s_barrier
	s_waitcnt lgkmcnt(0)
	s_setprio 1
	s_waitcnt lgkmcnt(0)
	v_mfma_f32_16x16x32_bf16 v[0:3], v[204:207], v[14:17], v[0:3]
	v_mfma_f32_16x16x32_bf16 v[104:107], v[208:211], v[18:21], v[0:3]
	v_mfma_f32_16x16x32_bf16 v[0:3], v[212:215], v[14:17], v[62:65]
	v_mfma_f32_16x16x32_bf16 v[108:111], v[224:227], v[18:21], v[0:3]
	v_mfma_f32_16x16x32_bf16 v[0:3], v[204:207], v[96:99], v[66:69]
	v_mfma_f32_16x16x32_bf16 v[88:91], v[208:211], v[100:103], v[0:3]
	v_mfma_f32_16x16x32_bf16 v[0:3], v[212:215], v[96:99], v[70:73]
	v_mfma_f32_16x16x32_bf16 v[92:95], v[224:227], v[100:103], v[0:3]
	v_mfma_f32_16x16x32_bf16 v[0:3], v[204:207], v[228:231], v[74:77]
	v_mfma_f32_16x16x32_bf16 v[56:59], v[208:211], v[232:235], v[0:3]
	v_mfma_f32_16x16x32_bf16 v[0:3], v[212:215], v[228:231], v[78:81]
	v_mfma_f32_16x16x32_bf16 v[60:63], v[224:227], v[232:235], v[0:3]
	v_mfma_f32_16x16x32_bf16 v[0:3], v[204:207], v[236:239], v[82:85]
	v_mfma_f32_16x16x32_bf16 v[32:35], v[208:211], v[240:243], v[0:3]
	v_mfma_f32_16x16x32_bf16 v[0:3], v[212:215], v[236:239], v[200:203]
	v_mfma_f32_16x16x32_bf16 v[36:39], v[224:227], v[240:243], v[0:3]
	s_setprio 0
	s_barrier
	ds_read_b128 v[200:203], v146
	ds_read_b128 v[244:247], v146 offset:1024
	ds_read_b128 v[248:251], v146 offset:2048
	ds_read_b128 v[144:147], v146 offset:3072
	s_waitcnt vmcnt(0)
	s_barrier
	s_waitcnt lgkmcnt(0)
	s_setprio 1
	s_waitcnt lgkmcnt(0)
	v_mfma_f32_16x16x32_bf16 v[0:3], v[200:203], v[14:17], v[10:13]
	v_mfma_f32_16x16x32_bf16 v[120:123], v[244:247], v[18:21], v[0:3]
	v_mfma_f32_16x16x32_bf16 v[0:3], v[248:251], v[14:17], v[136:139]
	v_mfma_f32_16x16x32_bf16 v[124:127], v[144:147], v[18:21], v[0:3]
	v_mfma_f32_16x16x32_bf16 v[0:3], v[200:203], v[96:99], v[140:143]
	v_mfma_f32_16x16x32_bf16 v[112:115], v[244:247], v[100:103], v[0:3]
	v_mfma_f32_16x16x32_bf16 v[0:3], v[248:251], v[96:99], v[152:155]
	v_mfma_f32_16x16x32_bf16 v[116:119], v[144:147], v[100:103], v[0:3]
	v_mfma_f32_16x16x32_bf16 v[0:3], v[200:203], v[228:231], v[40:43]
	v_mfma_f32_16x16x32_bf16 v[96:99], v[244:247], v[232:235], v[0:3]
	v_mfma_f32_16x16x32_bf16 v[0:3], v[248:251], v[228:231], v[44:47]
	v_mfma_f32_16x16x32_bf16 v[100:103], v[144:147], v[232:235], v[0:3]
	v_mfma_f32_16x16x32_bf16 v[0:3], v[200:203], v[236:239], v[48:51]
	v_mfma_f32_16x16x32_bf16 v[64:67], v[244:247], v[240:243], v[0:3]
	v_mfma_f32_16x16x32_bf16 v[0:3], v[248:251], v[236:239], v[52:55]
	v_mfma_f32_16x16x32_bf16 v[68:71], v[144:147], v[240:243], v[0:3]
	s_setprio 0
	s_barrier
	ds_read_b128 v[8:11], v183 offset:49152
	ds_read_b128 v[12:15], v183 offset:50176
	ds_read_b128 v[52:55], v183 offset:51200
	ds_read_b128 v[136:139], v183 offset:52224
	ds_read_b128 v[140:143], v183 offset:53248
	ds_read_b128 v[152:155], v183 offset:54272
	ds_read_b128 v[228:231], v183 offset:55296
	ds_read_b128 v[232:235], v183 offset:56320
	s_barrier
	s_waitcnt lgkmcnt(0)
	s_setprio 1
	s_waitcnt lgkmcnt(0)
	v_mfma_f32_16x16x32_bf16 v[0:3], v[204:207], v[8:11], v[4:7]
	v_mfma_f32_16x16x32_bf16 v[72:75], v[208:211], v[12:15], v[0:3]
	v_mfma_f32_16x16x32_bf16 v[0:3], v[212:215], v[8:11], v[156:159]
	v_mfma_f32_16x16x32_bf16 v[76:79], v[224:227], v[12:15], v[0:3]
	v_mfma_f32_16x16x32_bf16 v[0:3], v[204:207], v[52:55], v[160:163]
	v_mfma_f32_16x16x32_bf16 v[40:43], v[208:211], v[136:139], v[0:3]
	v_mfma_f32_16x16x32_bf16 v[0:3], v[212:215], v[52:55], v[164:167]
	v_mfma_f32_16x16x32_bf16 v[44:47], v[224:227], v[136:139], v[0:3]
	v_mfma_f32_16x16x32_bf16 v[0:3], v[204:207], v[140:143], v[168:171]
	v_mfma_f32_16x16x32_bf16 v[16:19], v[208:211], v[152:155], v[0:3]
	v_mfma_f32_16x16x32_bf16 v[0:3], v[212:215], v[140:143], v[172:175]
	v_mfma_f32_16x16x32_bf16 v[20:23], v[224:227], v[152:155], v[0:3]
	v_mfma_f32_16x16x32_bf16 v[0:3], v[204:207], v[228:231], v[216:219]
	v_mfma_f32_16x16x32_bf16 v[4:7], v[212:215], v[228:231], v[132:135]
	v_mfma_f32_16x16x32_bf16 v[0:3], v[208:211], v[232:235], v[0:3]
	v_mfma_f32_16x16x32_bf16 v[4:7], v[224:227], v[232:235], v[4:7]
	s_setprio 0
	s_setprio 1
	v_mfma_f32_16x16x32_bf16 v[48:51], v[200:203], v[8:11], v[220:223]
	v_mfma_f32_16x16x32_bf16 v[8:11], v[248:251], v[8:11], v[24:27]
	v_mfma_f32_16x16x32_bf16 v[84:87], v[144:147], v[12:15], v[8:11]
	v_mfma_f32_16x16x32_bf16 v[8:11], v[200:203], v[52:55], v[28:31]
	v_mfma_f32_16x16x32_bf16 v[80:83], v[244:247], v[12:15], v[48:51]
	v_mfma_f32_16x16x32_bf16 v[48:51], v[244:247], v[136:139], v[8:11]
	v_mfma_f32_16x16x32_bf16 v[8:11], v[248:251], v[52:55], v[176:179]
	v_mfma_f32_16x16x32_bf16 v[52:55], v[144:147], v[136:139], v[8:11]
	v_mfma_f32_16x16x32_bf16 v[8:11], v[200:203], v[140:143], v[184:187]
	v_mfma_f32_16x16x32_bf16 v[24:27], v[244:247], v[152:155], v[8:11]
	v_mfma_f32_16x16x32_bf16 v[8:11], v[248:251], v[140:143], v[188:191]
	v_mfma_f32_16x16x32_bf16 v[28:31], v[144:147], v[152:155], v[8:11]
	v_mfma_f32_16x16x32_bf16 v[8:11], v[200:203], v[228:231], v[192:195]
	v_mfma_f32_16x16x32_bf16 v[12:15], v[248:251], v[228:231], v[196:199]
	v_mfma_f32_16x16x32_bf16 v[8:11], v[244:247], v[232:235], v[8:11]
	v_mfma_f32_16x16x32_bf16 v[12:15], v[144:147], v[232:235], v[12:15]
	s_setprio 0
	s_cmpk_gt_u32 s0, 0xff
	s_barrier
	s_cbranch_scc1 .LBB0_261
	s_barrier
	s_branch .LBB0_261
